# indexer scoring per chunk: head-weighted sums with packed f32 fma, one lane-half swap per key half, single score write
# baseline (speedup 1.0000x reference)
.LBB0_105:
	s_lshl_b32 s1, s21, 4
	s_and_b32 s2, s1, 0x7f0
	s_and_b32 s0, s21, 0x100
	s_xor_b32 s6, s2, 0x7f0
	s_cmp_eq_u32 s0, 0
	s_cselect_b32 s2, s2, s6
	s_add_i32 s10, s2, s17
	s_and_b32 s33, s1, 0xfffff800
	s_add_i32 s6, s10, s33
	v_or_b32_e32 v2, s6, v249
	v_ashrrev_i32_e32 v3, 31, v2
	v_lshlrev_b64 v[2:3], 11, v[2:3]
	s_ashr_i32 s7, s6, 31
	v_lshl_add_u64 v[2:3], v[232:233], 0, v[2:3]
	s_lshl_b64 s[0:1], s[6:7], 6
	global_load_dwordx4 v[34:37], v[2:3], off
	global_load_dwordx4 v[38:41], v[2:3], off offset:32
	global_load_dwordx4 v[42:45], v[2:3], off offset:64
	global_load_dwordx4 v[46:49], v[2:3], off offset:96
	v_lshl_add_u64 v[2:3], v[238:239], 0, s[0:1]
	v_writelane_b32 v254, s6, 35
	s_or_b32 s0, s6, 1
	s_ashr_i32 s1, s0, 31
	s_lshl_b64 s[0:1], s[0:1], 6
	global_load_dwordx4 v[50:53], v[2:3], off
	global_load_dwordx4 v[54:57], v[2:3], off offset:32
	v_lshl_add_u64 v[2:3], v[238:239], 0, s[0:1]
	global_load_dwordx4 v[58:61], v[2:3], off
	global_load_dwordx4 v[62:65], v[2:3], off offset:32
	s_lshr_b32 s0, s2, 5
	s_add_i32 s0, s0, 2
	v_or_b32_e32 v2, s33, v248
	s_lshr_b32 s8, s0, 1
	v_ashrrev_i32_e32 v3, 31, v2
	s_add_i32 s9, s8, -1
	v_lshlrev_b64 v[2:3], 7, v[2:3]
	s_cmp_gt_u32 s2, 48
	v_lshl_add_u64 v[240:241], v[234:235], 0, v[2:3]
	s_cselect_b32 s2, 0x2000, 0
	v_lshl_add_u64 v[2:3], v[240:241], 0, s[2:3]
	s_movk_i32 s0, 0x1000
	v_add_co_u32_e32 v4, vcc, s0, v2
	v_writelane_b32 v254, s7, 36
	s_nop 0
	v_addc_co_u32_e32 v5, vcc, 0, v3, vcc
	v_add_co_u32_e32 v6, vcc, 0x1000, v240
	s_mov_b32 s2, 4
	s_nop 0
	v_addc_co_u32_e32 v7, vcc, 0, v241, vcc
	v_cndmask_b32_e64 v251, v250, v245, s[4:5]
	s_waitcnt vmcnt(0)
	s_waitcnt vmcnt(6)
	s_waitcnt vmcnt(5)
	s_waitcnt vmcnt(4)
	s_waitcnt vmcnt(3)
	s_waitcnt vmcnt(2)
	s_waitcnt vmcnt(1)
	s_waitcnt vmcnt(0)
	v_readlane_b32 s0, v253, 23
	s_lshl_b32 s1, s33, 7
	s_nop 3
	s_lshl_b32 s0, s0, 10
	v_lshl_add_u32 v74, v178, 4, s0
	s_add_u32 s6, s22, 0x32600000
	s_addc_u32 s7, s23, 0
	s_add_u32 s6, s6, s1
	s_addc_u32 s7, s7, 0
	v_mov_b32_e32 v75, 0
	v_lshl_add_u64 v[70:71], s[6:7], 0, v[74:75]
	s_movk_i32 s12, 0x90
	v_lshrrev_b32_e32 v76, 7, v74
	v_and_b32_e32 v77, 0x70, v74
	v_mad_u32_u24 v72, v76, s12, v77
	v_add_u32_e32 v72, 0x20200, v72
	v_lshrrev_b32_e32 v76, 5, v178
	v_lshlrev_b32_e32 v76, 4, v76
	v_mad_u32_u24 v73, v248, s12, v76
	v_add_u32_e32 v73, 0x20200, v73
	s_mov_b32 s12, 0x2000
	s_mov_b32 s13, 0
	global_load_dwordx4 v[66:69], v[70:71], off
	v_lshl_add_u64 v[70:71], v[70:71], 0, s[12:13]
	s_mov_b32 s2, 0
	s_mov_b32 s11, 0
	s_waitcnt vmcnt(0)
	ds_write_b128 v72, v[66:69]
	s_waitcnt lgkmcnt(0)
	s_cmp_lt_u32 s8, 2
	s_cbranch_scc1 .Lidx_pro1
	global_load_dwordx4 v[66:69], v[70:71], off
	v_lshl_add_u64 v[70:71], v[70:71], 0, s[12:13]

.Lidx_loop:
	v_add_u32_e32 v76, s11, v73
	ds_read_b128 v[118:121], v76
	ds_read_b128 v[126:129], v76 offset:4608
	ds_read_b128 v[114:117], v76 offset:32
	ds_read_b128 v[122:125], v76 offset:4640
	ds_read_b128 v[110:113], v76 offset:64
	ds_read_b128 v[106:109], v76 offset:4672
	ds_read_b128 v[86:89], v76 offset:4704
	ds_read_b128 v[102:105], v76 offset:96
	s_waitcnt lgkmcnt(6)
	v_mfma_f32_32x32x16_bf16 v[18:33], v[34:37], v[118:121], 0
	v_mfma_f32_32x32x16_bf16 v[2:17], v[34:37], v[126:129], 0
	s_waitcnt lgkmcnt(4)
	v_mfma_f32_32x32x16_bf16 v[18:33], v[38:41], v[114:117], v[18:33]
	v_mfma_f32_32x32x16_bf16 v[2:17], v[38:41], v[122:125], v[2:17]
	s_waitcnt lgkmcnt(2)
	v_mfma_f32_32x32x16_bf16 v[18:33], v[42:45], v[110:113], v[18:33]
	v_mfma_f32_32x32x16_bf16 v[2:17], v[42:45], v[106:109], v[2:17]
	s_waitcnt lgkmcnt(0)
	v_mfma_f32_32x32x16_bf16 v[2:17], v[46:49], v[86:89], v[2:17]
	v_mfma_f32_32x32x16_bf16 v[18:33], v[46:49], v[102:105], v[18:33]
	s_nop 10
	v_max_i32_e32 v2, 0, v2
	v_max_i32_e32 v3, 0, v3
	v_max_i32_e32 v4, 0, v4
	v_max_i32_e32 v5, 0, v5
	v_max_i32_e32 v6, 0, v6
	v_max_i32_e32 v7, 0, v7
	v_max_i32_e32 v8, 0, v8
	v_max_i32_e32 v9, 0, v9
	v_max_i32_e32 v10, 0, v10
	v_max_i32_e32 v11, 0, v11
	v_max_i32_e32 v12, 0, v12
	v_max_i32_e32 v13, 0, v13
	v_max_i32_e32 v14, 0, v14
	v_max_i32_e32 v15, 0, v15
	v_max_i32_e32 v16, 0, v16
	v_max_i32_e32 v17, 0, v17
	v_max_i32_e32 v18, 0, v18
	v_max_i32_e32 v19, 0, v19
	v_max_i32_e32 v20, 0, v20
	v_max_i32_e32 v21, 0, v21
	v_max_i32_e32 v22, 0, v22
	v_max_i32_e32 v23, 0, v23
	v_max_i32_e32 v24, 0, v24
	v_max_i32_e32 v25, 0, v25
	v_max_i32_e32 v26, 0, v26
	v_max_i32_e32 v27, 0, v27
	v_max_i32_e32 v28, 0, v28
	v_max_i32_e32 v29, 0, v29
	v_max_i32_e32 v30, 0, v30
	v_max_i32_e32 v31, 0, v31
	v_max_i32_e32 v32, 0, v32
	v_max_i32_e32 v33, 0, v33
	v_pk_mul_f32 v[78:79], v[50:51], v[2:3]
	v_pk_mul_f32 v[80:81], v[58:59], v[10:11]
	v_pk_mul_f32 v[82:83], v[50:51], v[18:19]
	v_pk_mul_f32 v[84:85], v[58:59], v[26:27]
	v_pk_fma_f32 v[78:79], v[52:53], v[4:5], v[78:79]
	v_pk_fma_f32 v[80:81], v[60:61], v[12:13], v[80:81]
	v_pk_fma_f32 v[82:83], v[52:53], v[20:21], v[82:83]
	v_pk_fma_f32 v[84:85], v[60:61], v[28:29], v[84:85]
	v_pk_fma_f32 v[78:79], v[54:55], v[6:7], v[78:79]
	v_pk_fma_f32 v[80:81], v[62:63], v[14:15], v[80:81]
	v_pk_fma_f32 v[82:83], v[54:55], v[22:23], v[82:83]
	v_pk_fma_f32 v[84:85], v[62:63], v[30:31], v[84:85]
	v_pk_fma_f32 v[78:79], v[56:57], v[8:9], v[78:79]
	v_pk_fma_f32 v[80:81], v[64:65], v[16:17], v[80:81]
	v_pk_fma_f32 v[82:83], v[56:57], v[24:25], v[82:83]
	v_pk_fma_f32 v[84:85], v[64:65], v[32:33], v[84:85]
	v_add_f32_e32 v2, v78, v79
	v_add_f32_e32 v10, v80, v81
	v_add_f32_e32 v18, v82, v83
	v_add_f32_e32 v26, v84, v85
	s_nop 1
	v_permlane32_swap_b32_e32 v18, v26
	v_permlane32_swap_b32_e32 v2, v10
	v_add_f32_e32 v18, v18, v26
	v_add_f32_e32 v2, v2, v10
	ds_write2_b32 v251, v18, v2 offset1:32
	v_add_u32_e32 v251, 0x100, v251
	s_add_i32 s2, s2, 1
	s_cmp_ge_u32 s2, s8
	s_cbranch_scc1 .Lidx_done
	s_xor_b32 s11, s11, 0x2400
	s_waitcnt vmcnt(0)
	v_add_u32_e32 v76, s11, v72
	ds_write_b128 v76, v[66:69]
	s_waitcnt lgkmcnt(0)
	s_add_i32 s0, s2, 1
	s_cmp_ge_u32 s0, s8
	s_cbranch_scc1 .Lidx_nold
	global_load_dwordx4 v[66:69], v[70:71], off
	v_lshl_add_u64 v[70:71], v[70:71], 0, s[12:13]
